# prologue: sample rows of the first rmsnorm handled by the 64 waves without a weight item instead of a fifth trip on workgroups 0..31
# speedup vs baseline: 1.0083x; 1.0016x over previous
.LBB0_1033:
	s_and_b64 vcc, exec, s[2:3]
	v_readlane_b32 s26, v254, 45
	v_readlane_b32 s27, v254, 46
	s_cbranch_vccz .LBB0_1094
	s_waitcnt vmcnt(0)
	s_mov_b32 s32, 0
	v_readlane_b32 s31, v251, 8
	s_movk_i32 s30, 0x2400
	s_movk_i32 s29, 0x40ff
	s_cmp_lg_u32 s31, 0
	s_cselect_b32 s31, 0x7c0, s30
	s_cselect_b32 s28, 0, 1
	s_cselect_b32 s29, 0x3fff, s29
	s_mov_b32 s30, s6
	v_mov_b32_e32 v35, v178
	s_movk_i32 s2, 0x4100
	v_ashrrev_i32_e32 v47, 6, v35
	v_and_b32_e32 v34, 63, v35
	v_add_u32_e32 v46, s88, v47
	v_cmp_gt_i32_e32 vcc, s2, v46
	v_lshlrev_b32_e32 v36, 3, v34
	s_and_saveexec_b64 s[2:3], vcc
	s_cbranch_execz .Lxn_done
.Lxn_body:
	v_cmp_lt_i32_e32 vcc, v186, v250
	v_readlane_b32 s12, v254, 47
	v_mov_b32_e32 v37, v1
	v_cndmask_b32_e32 v0, v185, v186, vcc
	v_cmp_lt_i32_e32 vcc, v191, v250
	v_lshlrev_b32_e32 v48, 2, v0
	v_readlane_b32 s13, v254, 48
	v_cndmask_b32_e32 v0, v185, v191, vcc
	v_mov_b32_e32 v2, 0
	v_lshlrev_b32_e32 v49, 2, v0
	v_lshl_add_u64 v[38:39], s[12:13], 0, v[36:37]
	s_mov_b64 s[14:15], 0
	v_mov_b32_e32 v42, v46
	v_mov_b32_e32 v3, v2
	v_mov_b32_e32 v4, v2
	v_mov_b32_e32 v5, v2
	v_mov_b32_e32 v6, v2
	v_mov_b32_e32 v7, v2
	v_mov_b32_e32 v8, v2
	v_mov_b32_e32 v9, v2
	v_mov_b32_e32 v10, v2
	v_mov_b32_e32 v11, v2
	v_mov_b32_e32 v12, v2
	v_mov_b32_e32 v13, v2
	v_mov_b32_e32 v14, v2
	v_mov_b32_e32 v15, v2
	v_mov_b32_e32 v16, v2
	v_mov_b32_e32 v17, v2
	s_branch .LBB0_1037
.LBB0_1036:
	s_or_b64 exec, exec, s[18:19]
	v_add_u32_e32 v42, s30, v40
	s_mov_b32 s18, s29
	v_cmp_lt_i32_e32 vcc, s18, v42
	s_or_b64 s[14:15], vcc, s[14:15]
	s_andn2_b64 exec, exec, s[14:15]
	s_cbranch_execz .Lxn_done
.LBB0_1037:
	v_add_u32_e32 v0, 0xffffc000, v42
	v_ashrrev_i32_e32 v43, 31, v42
	v_cmp_gt_i32_e32 vcc, s5, v42
	v_mov_b32_e32 v24, s39
	v_mov_b32_e32 v25, s37
	v_cndmask_b32_e32 v19, 0, v43, vcc
	v_cndmask_b32_e32 v18, v0, v42, vcc
	v_mov_b32_e32 v26, s38
	v_mov_b32_e32 v27, s36
	v_cndmask_b32_e32 v21, v24, v25, vcc
	v_cndmask_b32_e32 v20, v26, v27, vcc
	v_lshlrev_b64 v[18:19], 12, v[18:19]
	v_lshl_add_u64 v[18:19], v[20:21], 0, v[18:19]
	v_lshlrev_b32_e32 v0, 4, v34
	v_lshl_add_u64 v[30:31], v[18:19], 0, v[0:1]
	global_load_dwordx4 v[18:21], v[30:31], off
	v_add_u32_e32 v40, s30, v42
	v_add_u32_e32 v22, 0xffffc000, v40
	v_ashrrev_i32_e32 v41, 31, v40
	v_cmp_gt_i32_e32 vcc, s5, v40
	s_movk_i32 s12, 0x4100
	s_nop 0
	v_cndmask_b32_e32 v23, 0, v41, vcc
	v_cndmask_b32_e32 v22, v22, v40, vcc
	v_cndmask_b32_e32 v25, v24, v25, vcc
	v_cndmask_b32_e32 v24, v26, v27, vcc
	v_lshlrev_b64 v[22:23], 12, v[22:23]
	v_lshl_add_u64 v[44:45], v[24:25], 0, v[22:23]
	v_cmp_gt_i32_e32 vcc, s12, v40
	s_and_saveexec_b64 s[18:19], vcc
	s_cbranch_execnz .LBB0_1044
	s_or_b64 exec, exec, s[18:19]
	global_load_dwordx4 v[22:25], v[30:31], off offset:1024
	s_and_saveexec_b64 s[18:19], vcc
	s_cbranch_execnz .LBB0_1045

.Lxn_done:
	s_or_b64 exec, exec, s[2:3]
	s_cmp_lg_u32 s28, 0
	s_cbranch_scc1 .Lxn_fin
	s_mov_b32 s28, 1
	s_movk_i32 s30, 64
	s_movk_i32 s29, 0x40ff
	v_add_u32_e32 v46, s88, v47
	v_add_u32_e32 v0, 0x3840, v46
	s_movk_i32 s2, 0x7c0
	v_cmp_gt_i32_e32 vcc, s2, v46
	v_mov_b32_e32 v46, 0x4100
	v_cndmask_b32_e32 v46, v0, v46, vcc
	s_movk_i32 s2, 0x4100
	v_cmp_gt_i32_e32 vcc, s2, v46
	s_and_saveexec_b64 s[2:3], vcc
	s_cbranch_execz .Lxn_done
	s_branch .Lxn_body
.Lxn_fin:
	s_mov_b32 s30, s6
	v_add_u32_e32 v46, s88, v47
